# job0 (prompt FoX) PV: sixteen transposed V fragment reads per 64-key step issued up front, MFMA pairs straight-line with counted waits
# baseline (speedup 1.0000x reference)
.LBB0_1070:
	s_nop 3
	v_add_u32_e32 v90, v197, v200
	ds_read_b64_tr_b16 v[220:221], v90 offset:9216
	ds_read_b64_tr_b16 v[222:223], v90 offset:10368
	ds_read_b64_tr_b16 v[224:225], v90 offset:9280
	ds_read_b64_tr_b16 v[226:227], v90 offset:10432
	ds_read_b64_tr_b16 v[228:229], v90 offset:11520
	ds_read_b64_tr_b16 v[230:231], v90 offset:12672
	ds_read_b64_tr_b16 v[232:233], v90 offset:11584
	ds_read_b64_tr_b16 v[234:235], v90 offset:12736
	ds_read_b64_tr_b16 v[236:237], v90 offset:13824
	ds_read_b64_tr_b16 v[238:239], v90 offset:14976
	ds_read_b64_tr_b16 v[240:241], v90 offset:13888
	ds_read_b64_tr_b16 v[242:243], v90 offset:15040
	ds_read_b64_tr_b16 v[246:247], v90 offset:16128
	ds_read_b64_tr_b16 v[248:249], v90 offset:17280
	ds_read_b64_tr_b16 v[250:251], v90 offset:16192
	ds_read_b64_tr_b16 v[252:253], v90 offset:17344
	s_and_b64 vcc, exec, s[12:13]
	s_cbranch_vccnz .Lj0p1_a0
	s_waitcnt lgkmcnt(14)
	v_mfma_f32_32x32x16_bf16 v[50:65], v[220:223], v[110:113], v[50:65]
	s_waitcnt lgkmcnt(12)
	v_mfma_f32_32x32x16_bf16 v[34:49], v[224:227], v[110:113], v[34:49]
.Lj0p1_a0:
	s_and_b64 vcc, exec, s[10:11]
	s_cbranch_vccnz .Lj0p1_b0
	s_waitcnt lgkmcnt(14)
	v_mfma_f32_32x32x16_bf16 v[2:17], v[220:223], v[78:81], v[2:17]
	s_waitcnt lgkmcnt(12)
	v_mfma_f32_32x32x16_bf16 v[18:33], v[224:227], v[78:81], v[18:33]
.Lj0p1_b0:
	s_and_b64 vcc, exec, s[12:13]
	s_cbranch_vccnz .Lj0p1_a1
	s_waitcnt lgkmcnt(10)
	v_mfma_f32_32x32x16_bf16 v[50:65], v[228:231], v[106:109], v[50:65]
	s_waitcnt lgkmcnt(8)
	v_mfma_f32_32x32x16_bf16 v[34:49], v[232:235], v[106:109], v[34:49]
.Lj0p1_a1:
	s_and_b64 vcc, exec, s[10:11]
	s_cbranch_vccnz .Lj0p1_b1
	s_waitcnt lgkmcnt(10)
	v_mfma_f32_32x32x16_bf16 v[2:17], v[228:231], v[74:77], v[2:17]
	s_waitcnt lgkmcnt(8)
	v_mfma_f32_32x32x16_bf16 v[18:33], v[232:235], v[74:77], v[18:33]
.Lj0p1_b1:
	s_and_b64 vcc, exec, s[12:13]
	s_cbranch_vccnz .Lj0p1_a2
	s_waitcnt lgkmcnt(6)
	v_mfma_f32_32x32x16_bf16 v[50:65], v[236:239], v[102:105], v[50:65]
	s_waitcnt lgkmcnt(4)
	v_mfma_f32_32x32x16_bf16 v[34:49], v[240:243], v[102:105], v[34:49]
.Lj0p1_a2:
	s_and_b64 vcc, exec, s[10:11]
	s_cbranch_vccnz .Lj0p1_b2
	s_waitcnt lgkmcnt(6)
	v_mfma_f32_32x32x16_bf16 v[2:17], v[236:239], v[70:73], v[2:17]
	s_waitcnt lgkmcnt(4)
	v_mfma_f32_32x32x16_bf16 v[18:33], v[240:243], v[70:73], v[18:33]
.Lj0p1_b2:
	s_and_b64 vcc, exec, s[12:13]
	s_cbranch_vccnz .Lj0p1_a3
	s_waitcnt lgkmcnt(2)
	v_mfma_f32_32x32x16_bf16 v[50:65], v[246:249], v[98:101], v[50:65]
	s_waitcnt lgkmcnt(0)
	v_mfma_f32_32x32x16_bf16 v[34:49], v[250:253], v[98:101], v[34:49]
.Lj0p1_a3:
	s_and_b64 vcc, exec, s[10:11]
	s_cbranch_vccnz .Lj0p1_b3
	s_waitcnt lgkmcnt(2)
	v_mfma_f32_32x32x16_bf16 v[2:17], v[246:249], v[66:69], v[2:17]
	s_waitcnt lgkmcnt(0)
	v_mfma_f32_32x32x16_bf16 v[18:33], v[250:253], v[66:69], v[18:33]
.Lj0p1_b3:
.LBB0_1086:
	s_add_i32 s12, s67, 1
	s_cmp_lt_u32 s12, s59
	s_cselect_b64 s[10:11], -1, 0
	s_cmp_ge_u32 s12, s59
	s_cbranch_scc1 .LBB0_1090
	s_waitcnt vmcnt(1)
	ds_write_b128 v194, v[170:173] offset:32768
	s_waitcnt vmcnt(0)
	ds_write_b128 v194, v[174:177] offset:41984
	s_and_saveexec_b64 s[12:13], s[8:9]
	v_xor_b32_e32 v208, 0x80000000, v192
	ds_write_b32 v195, v208 offset:51200
	s_or_b64 exec, exec, s[12:13]

.LBB0_1127:
	s_nop 3
	v_add_u32_e32 v90, v197, v200
	ds_read_b64_tr_b16 v[220:221], v90 offset:41984
	ds_read_b64_tr_b16 v[222:223], v90 offset:43136
	ds_read_b64_tr_b16 v[224:225], v90 offset:42048
	ds_read_b64_tr_b16 v[226:227], v90 offset:43200
	ds_read_b64_tr_b16 v[228:229], v90 offset:44288
	ds_read_b64_tr_b16 v[230:231], v90 offset:45440
	ds_read_b64_tr_b16 v[232:233], v90 offset:44352
	ds_read_b64_tr_b16 v[234:235], v90 offset:45504
	ds_read_b64_tr_b16 v[236:237], v90 offset:46592
	ds_read_b64_tr_b16 v[238:239], v90 offset:47744
	ds_read_b64_tr_b16 v[240:241], v90 offset:46656
	ds_read_b64_tr_b16 v[242:243], v90 offset:47808
	ds_read_b64_tr_b16 v[246:247], v90 offset:48896
	ds_read_b64_tr_b16 v[248:249], v90 offset:50048
	ds_read_b64_tr_b16 v[250:251], v90 offset:48960
	ds_read_b64_tr_b16 v[252:253], v90 offset:50112
	s_and_b64 vcc, exec, s[12:13]
	s_cbranch_vccnz .Lj0p2_a0
	s_waitcnt lgkmcnt(14)
	v_mfma_f32_32x32x16_bf16 v[50:65], v[220:223], v[110:113], v[50:65]
	s_waitcnt lgkmcnt(12)
	v_mfma_f32_32x32x16_bf16 v[34:49], v[224:227], v[110:113], v[34:49]

.Lj0p2_b3:
.LBB0_1141:
	s_cmp_ge_u32 s67, s62
	s_cbranch_scc1 .LBB0_1145

.LBB0_1146:
	s_mov_b32 s67, s66
	s_branch .LBB0_1035
.LBB0_1149:
	s_add_i32 s53, s53, s3
	s_cmpk_gt_i32 s53, 0xff
	s_cbranch_scc1 .LBB0_918
